# EpiFin: final-norm gains requested before the four-workgroup meet
# baseline (speedup 1.0000x reference)
; __device__ __forceinline__ unsigned xb_ld(unsigned* p)              { return __hip_atomic_load(p, __ATOMIC_RELAXED, __HIP_MEMORY_SCOPE_AGENT); }
; __device__ __forceinline__ unsigned xb_add(unsigned* p, unsigned v) { return __hip_atomic_fetch_add(p, v, __ATOMIC_RELAXED, __HIP_MEMORY_SCOPE_AGENT); }
; #define XB_SPIN(cond, bar) do { unsigned _sp = 0; while (cond) { __builtin_amdgcn_s_sleep(1); \
;     if ((++_sp & 255u) == 0u) { if (xb_ld(&(bar)[XB_TMO])) break; if (_sp > XB_SPIN_CAP) { atomicAdd(&(bar)[XB_TMO], 1u); break; } } } } while (0)
;     __device__ __forceinline__ void operator()(const f32x4 (&acc_)[2][2][4][2], const Unit& u, int wr, int wc, int fr, int fq) const {
;     ...
;         asm volatile("s_waitcnt vmcnt(0)" ::: "memory");
;         __syncthreads();
;         if (threadIdx.x == 0) {
;             (void)xb_add(&cnt[upm * 64], 1u);
;             XB_SPIN(xb_ld(&cnt[upm * 64]) < nteam, bar);
;             __builtin_amdgcn_fence(__ATOMIC_ACQUIRE, "agent");
;             asm volatile("s_waitcnt vmcnt(0)" ::: "memory");
;         }
;         __syncthreads();
;         { int t_ = threadIdx.x; asm volatile("" : "+v"(t_)); if (t_ < 256) rt2[t_] = rinv16(ssq_out, upm * BM + t_, 1.0f / 1024.0f); }
;         __syncthreads();
;         f32x4 gq[2][2];
; #pragma unroll
;         for (int bj = 0; bj < 2; ++bj) { gq[bj][0] = *(const f32x4*)(gfin + col0 + bj * HALF); gq[bj][1] = *(const f32x4*)(gfin + col0 + bj * HALF + 4); }
.LBB0_2074:
	s_or_b64 exec, exec, s[22:23]
	s_waitcnt vmcnt(0)
	s_barrier
	v_lshl_add_u64 v[212:213], v[4:5], 2, s[28:29]
	global_load_dwordx4 v[216:219], v[212:213], off offset:16
	global_load_dwordx4 v[220:223], v[212:213], off
	global_load_dwordx4 v[224:227], v[212:213], off offset:528
	global_load_dwordx4 v[228:231], v[212:213], off offset:512
	s_mov_b64 s[0:1], exec
	v_readlane_b32 s22, v252, 45
	v_readlane_b32 s23, v252, 46
	s_and_b64 s[22:23], s[0:1], s[22:23]
	s_mov_b64 exec, s[22:23]
	s_cbranch_execz .LBB0_2091
	s_lshl_b32 s22, s41, 6
	s_mov_b64 s[24:25], exec
	s_ashr_i32 s23, s22, 31
	s_lshl_b64 s[22:23], s[22:23], 2
	v_readlane_b32 s36, v253, 41
	v_mbcnt_lo_u32_b32 v2, s24, 0
	s_add_u32 s22, s36, s22
	v_readlane_b32 s36, v253, 33
	v_mbcnt_hi_u32_b32 v2, s25, v2
	s_addc_u32 s23, s36, s23
	v_cmp_eq_u32_e32 vcc, 0, v2
	s_and_saveexec_b64 s[42:43], vcc
	s_cbranch_execz .LBB0_2077
	s_bcnt1_i32_b64 s24, s[24:25]
	v_mov_b32_e32 v2, s24
	global_atomic_add v3, v2, s[22:23]

; #define PG8_LAS __attribute__((address_space(3)))
;     __device__ __forceinline__ void operator()(const f32x4 (&acc_)[2][2][4][2], const Unit& u, int wr, int wc, int fr, int fq) const {
;     ...
;         { int t_ = threadIdx.x; asm volatile("" : "+v"(t_)); if (t_ < 256) rt2[t_] = rinv16(ssq_out, upm * BM + t_, 1.0f / 1024.0f); }
;         __syncthreads();
;         f32x4 gq[2][2];
; #pragma unroll
;         for (int bj = 0; bj < 2; ++bj) { gq[bj][0] = *(const f32x4*)(gfin + col0 + bj * HALF); gq[bj][1] = *(const f32x4*)(gfin + col0 + bj * HALF + 4); }
;         PG8_LAS float* stg = (PG8_LAS float*)ring; const int wave = wr * 4 + wc, lane = fr + 16 * fq;
; #pragma unroll
;         for (int ai = 0; ai < 2; ++ai) {
; #pragma unroll
;             for (int m = 0; m < 4; ++m) { const int rl = wr * 64 + m * 16 + fr; const float r = rt2[rl + ai * HALF];
; #pragma unroll
;                 for (int bj = 0; bj < 2; ++bj)
; #pragma unroll
;                     for (int n = 0; n < 2; ++n) { const int c16 = (bj * 32 + wc * 8 + 2 * fq + n) ^ fr;
;                         *(PG8_LAS f32x4*)(stg + rl * 256 + c16 * 4) = acc[ai][bj][m][n] * r * gq[bj][n]; } }
.LBB0_2093:
	s_or_b64 exec, exec, s[0:1]
	v_lshl_add_u64 v[4:5], v[4:5], 2, s[28:29]
	s_waitcnt lgkmcnt(0)
	s_barrier
	s_waitcnt vmcnt(0)
	v_mov_b64_e32 v[138:139], v[216:217]
	v_mov_b64_e32 v[140:141], v[218:219]
	v_mov_b64_e32 v[146:147], v[220:221]
	v_mov_b64_e32 v[148:149], v[222:223]
	v_mov_b64_e32 v[134:135], v[224:225]
	v_mov_b64_e32 v[136:137], v[226:227]
	v_mov_b64_e32 v[142:143], v[228:229]
	v_mov_b64_e32 v[144:145], v[230:231]
	ds_read_b32 v2, v190
	s_add_i32 s0, s7, s9
	s_ashr_i32 s41, s40, 31
	s_ashr_i32 s1, s0, 31
	s_lshl_b64 s[22:23], s[0:1], 12
	s_waitcnt lgkmcnt(0)
	v_pk_mul_f32 v[4:5], v[132:133], v[2:3] op_sel_hi:[1,0]
	v_pk_mul_f32 v[150:151], v[130:131], v[2:3] op_sel_hi:[1,0]
	v_pk_mul_f32 v[154:155], v[98:99], v[2:3] op_sel_hi:[1,0]
	v_pk_mul_f32 v[156:157], v[66:67], v[2:3] op_sel_hi:[1,0]
	s_lshl_b64 s[0:1], s[40:41], 2
	s_add_u32 s22, s22, s0
	s_addc_u32 s23, s23, s1
	s_add_u32 s22, s26, s22
	s_addc_u32 s23, s27, s23
	s_mov_b32 s24, 0
	s_waitcnt vmcnt(2)
	v_pk_mul_f32 v[152:153], v[148:149], v[4:5]
	v_pk_mul_f32 v[150:151], v[146:147], v[150:151]
	v_add_u32_e32 v4, v191, v185
	ds_write_b128 v4, v[150:153]
	v_pk_mul_f32 v[150:151], v[100:101], v[2:3] op_sel_hi:[1,0]
	v_add_u32_e32 v5, v191, v186
	v_pk_mul_f32 v[152:153], v[140:141], v[150:151]
	v_pk_mul_f32 v[150:151], v[138:139], v[154:155]
	ds_write_b128 v5, v[150:153]
	v_pk_mul_f32 v[150:151], v[116:117], v[2:3] op_sel_hi:[1,0]
	v_pk_mul_f32 v[152:153], v[114:115], v[2:3] op_sel_hi:[1,0]
	s_waitcnt vmcnt(0)
	v_pk_mul_f32 v[154:155], v[144:145], v[150:151]
	v_pk_mul_f32 v[152:153], v[142:143], v[152:153]
	v_add_u32_e32 v150, v191, v187
	ds_write_b128 v150, v[152:155]
	v_pk_mul_f32 v[152:153], v[68:69], v[2:3] op_sel_hi:[1,0]
	v_add_u32_e32 v151, v191, v188
	v_pk_mul_f32 v[154:155], v[136:137], v[152:153]
	v_pk_mul_f32 v[152:153], v[134:135], v[156:157]
	ds_write_b128 v151, v[152:155]
	ds_read_b32 v2, v192
	s_waitcnt lgkmcnt(0)
	v_pk_mul_f32 v[152:153], v[128:129], v[2:3] op_sel_hi:[1,0]
	v_pk_mul_f32 v[154:155], v[126:127], v[2:3] op_sel_hi:[1,0]
	v_pk_mul_f32 v[156:157], v[148:149], v[152:153]
	v_pk_mul_f32 v[154:155], v[146:147], v[154:155]
	v_add_u32_e32 v152, v193, v185
	ds_write_b128 v152, v[154:157]
	v_pk_mul_f32 v[154:155], v[92:93], v[2:3] op_sel_hi:[1,0]
	v_pk_mul_f32 v[158:159], v[90:91], v[2:3] op_sel_hi:[1,0]
	v_pk_mul_f32 v[156:157], v[140:141], v[154:155]
	v_pk_mul_f32 v[154:155], v[138:139], v[158:159]
	v_add_u32_e32 v153, v193, v186
	ds_write_b128 v153, v[154:157]
	v_pk_mul_f32 v[154:155], v[112:113], v[2:3] op_sel_hi:[1,0]
	v_pk_mul_f32 v[156:157], v[110:111], v[2:3] op_sel_hi:[1,0]
	v_pk_mul_f32 v[158:159], v[144:145], v[154:155]
	v_pk_mul_f32 v[156:157], v[142:143], v[156:157]
	v_add_u32_e32 v154, v193, v187
	ds_write_b128 v154, v[156:159]
	v_pk_mul_f32 v[156:157], v[60:61], v[2:3] op_sel_hi:[1,0]
	v_pk_mul_f32 v[160:161], v[58:59], v[2:3] op_sel_hi:[1,0]
	v_pk_mul_f32 v[158:159], v[136:137], v[156:157]
	v_pk_mul_f32 v[156:157], v[134:135], v[160:161]
	v_add_u32_e32 v155, v193, v188
	ds_write_b128 v155, v[156:159]
	ds_read_b32 v2, v194
	s_waitcnt lgkmcnt(0)
	v_pk_mul_f32 v[156:157], v[124:125], v[2:3] op_sel_hi:[1,0]
	v_pk_mul_f32 v[158:159], v[122:123], v[2:3] op_sel_hi:[1,0]
	v_pk_mul_f32 v[160:161], v[148:149], v[156:157]
	v_pk_mul_f32 v[158:159], v[146:147], v[158:159]
	v_add_u32_e32 v156, v195, v185
	ds_write_b128 v156, v[158:161]
	v_pk_mul_f32 v[158:159], v[84:85], v[2:3] op_sel_hi:[1,0]
	v_pk_mul_f32 v[162:163], v[82:83], v[2:3] op_sel_hi:[1,0]
	v_pk_mul_f32 v[160:161], v[140:141], v[158:159]
	v_pk_mul_f32 v[158:159], v[138:139], v[162:163]
	v_add_u32_e32 v157, v195, v186
	ds_write_b128 v157, v[158:161]
	v_pk_mul_f32 v[158:159], v[108:109], v[2:3] op_sel_hi:[1,0]
	v_pk_mul_f32 v[160:161], v[106:107], v[2:3] op_sel_hi:[1,0]
	v_pk_mul_f32 v[162:163], v[144:145], v[158:159]
	v_pk_mul_f32 v[160:161], v[142:143], v[160:161]
	v_add_u32_e32 v158, v195, v187
	ds_write_b128 v158, v[160:163]
	v_pk_mul_f32 v[160:161], v[52:53], v[2:3] op_sel_hi:[1,0]
	v_pk_mul_f32 v[164:165], v[50:51], v[2:3] op_sel_hi:[1,0]
	v_pk_mul_f32 v[162:163], v[136:137], v[160:161]
	v_pk_mul_f32 v[160:161], v[134:135], v[164:165]
	v_add_u32_e32 v159, v195, v188
	ds_write_b128 v159, v[160:163]
	ds_read_b32 v2, v196
	s_waitcnt lgkmcnt(0)
	v_pk_mul_f32 v[160:161], v[120:121], v[2:3] op_sel_hi:[1,0]
	v_pk_mul_f32 v[162:163], v[118:119], v[2:3] op_sel_hi:[1,0]
	v_pk_mul_f32 v[164:165], v[148:149], v[160:161]
	v_pk_mul_f32 v[162:163], v[146:147], v[162:163]
	v_add_u32_e32 v160, v197, v185
	ds_write_b128 v160, v[162:165]
	v_pk_mul_f32 v[162:163], v[76:77], v[2:3] op_sel_hi:[1,0]
	v_pk_mul_f32 v[174:175], v[74:75], v[2:3] op_sel_hi:[1,0]
	v_pk_mul_f32 v[164:165], v[140:141], v[162:163]
	v_pk_mul_f32 v[162:163], v[138:139], v[174:175]
	v_add_u32_e32 v161, v197, v186
	ds_write_b128 v161, v[162:165]
	v_pk_mul_f32 v[162:163], v[104:105], v[2:3] op_sel_hi:[1,0]
	v_pk_mul_f32 v[164:165], v[102:103], v[2:3] op_sel_hi:[1,0]
	v_pk_mul_f32 v[176:177], v[144:145], v[162:163]
	v_pk_mul_f32 v[174:175], v[142:143], v[164:165]
	v_add_u32_e32 v162, v197, v187
	ds_write_b128 v162, v[174:177]
	v_pk_mul_f32 v[164:165], v[44:45], v[2:3] op_sel_hi:[1,0]
	v_pk_mul_f32 v[174:175], v[42:43], v[2:3] op_sel_hi:[1,0]
	v_pk_mul_f32 v[176:177], v[136:137], v[164:165]
	v_pk_mul_f32 v[174:175], v[134:135], v[174:175]
	v_add_u32_e32 v163, v197, v188
	v_mov_b32_e32 v164, v198
	ds_write_b128 v163, v[174:177]
	s_waitcnt lgkmcnt(0)
	s_barrier
